# mLSTM output-norm loop handles two items per trip (both items loads in flight together); chunkwise mLSTM output step reads its 16 LDS terms in one batch
# speedup vs baseline: 1.0044x; 1.0044x over previous
.LBB0_395:
	s_cmp_lg_u32 0, -1
	s_cselect_b32 s2, 0, 0
	s_add_i32 s2, s2, 0x14000
	v_add_u32_e32 v56, s2, v193
	ds_read_b64_tr_b16 v[4:5], v56 offset:0
	ds_read_b64_tr_b16 v[6:7], v56 offset:0x800
	ds_read_b64_tr_b16 v[8:9], v56 offset:0x1000
	v_pk_mul_f32 v[32:33], v[32:33], v[2:3] op_sel_hi:[1,0]
	v_pk_mul_f32 v[30:31], v[30:31], v[2:3] op_sel_hi:[1,0]
	v_pk_mul_f32 v[28:29], v[28:29], v[2:3] op_sel_hi:[1,0]
	v_pk_mul_f32 v[26:27], v[26:27], v[2:3] op_sel_hi:[1,0]
	v_pk_mul_f32 v[24:25], v[24:25], v[2:3] op_sel_hi:[1,0]
	v_pk_mul_f32 v[22:23], v[22:23], v[2:3] op_sel_hi:[1,0]
	v_pk_mul_f32 v[20:21], v[20:21], v[2:3] op_sel_hi:[1,0]
	v_pk_mul_f32 v[18:19], v[18:19], v[2:3] op_sel_hi:[1,0]
	ds_read_b64_tr_b16 v[10:11], v56 offset:0x1800
	v_lshlrev_b32_e32 v2, 2, v186
	v_and_b32_e32 v55, 16, v186
	ds_read_b64_tr_b16 v[12:13], v56 offset:0x2000
	v_and_b32_e32 v2, 12, v2
	v_bfe_u32 v54, v186, 2, 2
	ds_read_b64_tr_b16 v[14:15], v56 offset:0x2800
	v_or3_b32 v2, v55, v2, s33
	v_lshlrev_b32_e32 v103, 3, v188
	ds_read_b64_tr_b16 v[50:51], v56 offset:0x3000
	v_or_b32_e32 v55, v103, v54
	v_lshlrev_b32_e32 v2, 1, v2
	v_lshlrev_b32_e32 v54, 4, v54
	ds_read_b64_tr_b16 v[52:53], v56 offset:0x3800
	v_lshlrev_b32_e32 v56, 8, v55
	v_bitop3_b32 v54, v2, v54, s56 bitop3:0x6c
	v_add3_u32 v104, v56, s46, v54
	v_or_b32_e32 v54, 4, v55
	v_lshlrev_b32_e32 v55, 8, v54
	v_lshlrev_b32_e32 v54, 4, v54
	v_and_b32_e32 v54, 0x70, v54
	v_bitop3_b32 v2, v2, v54, s56 bitop3:0x6c
	v_add3_u32 v2, v55, s46, v2
	ds_read_b64_tr_b16 v[54:55], v104 offset:0
	ds_read_b64_tr_b16 v[56:57], v2 offset:0
	ds_read_b64_tr_b16 v[58:59], v104 offset:0x1000
	ds_read_b64_tr_b16 v[60:61], v2 offset:0x1000
	ds_read_b64_tr_b16 v[62:63], v104 offset:0x2000
	ds_read_b64_tr_b16 v[64:65], v2 offset:0x2000
	ds_read_b64_tr_b16 v[192:193], v104 offset:0x3000
	ds_read_b64_tr_b16 v[194:195], v2 offset:0x3000
	s_waitcnt lgkmcnt(0)
	s_nop 0
	v_mfma_f32_32x32x16_bf16 v[18:33], v[54:57], v[4:7], v[18:33]
	s_add_i32 s2, 0, 0x18000
	v_add_u32_e32 v7, s47, v103
	v_mov_b32_e32 v2, 1.0
	v_add_u32_e32 v6, s2, v190
	v_add_u32_e32 v4, 16, v7
	s_waitcnt lgkmcnt(0)
	s_barrier
	v_mfma_f32_32x32x16_bf16 v[18:33], v[58:61], v[8:11], v[18:33]
	v_xad_u32 v10, v4, v189, v6
	v_xad_u32 v8, v7, v189, v6
	v_add_u32_e32 v9, 32, v7
	s_andn2_b64 vcc, exec, s[28:29]
	v_mfma_f32_32x32x16_bf16 v[18:33], v[62:65], v[12:15], v[18:33]
	v_mfma_f32_32x32x16_bf16 v[18:33], v[192:195], v[50:53], v[18:33]
	s_nop 11
	v_mul_f32_e32 v4, v18, v2
	v_mul_f32_e32 v5, v19, v2
	v_mul_f32_e32 v11, v20, v2
	v_mul_f32_e32 v12, v21, v2
	v_cvt_pk_bf16_f32 v4, v4, v5
	v_cvt_pk_bf16_f32 v5, v11, v12
	v_mul_f32_e32 v13, v22, v2
	v_mul_f32_e32 v14, v23, v2
	v_mul_f32_e32 v15, v24, v2
	v_mul_f32_e32 v50, v25, v2
	ds_write_b64 v8, v[4:5]
	v_cvt_pk_bf16_f32 v4, v13, v14
	v_cvt_pk_bf16_f32 v5, v15, v50
	v_mul_f32_e32 v51, v26, v2
	v_mul_f32_e32 v52, v27, v2
	v_mul_f32_e32 v53, v28, v2
	v_mul_f32_e32 v54, v29, v2
	ds_write_b64 v10, v[4:5]
	v_cvt_pk_bf16_f32 v4, v51, v52
	v_cvt_pk_bf16_f32 v5, v53, v54
	v_xad_u32 v8, v9, v189, v6
	ds_write_b64 v8, v[4:5]
	v_mul_f32_e32 v4, v30, v2
	v_mul_f32_e32 v5, v31, v2
	v_cvt_pk_bf16_f32 v4, v4, v5
	v_mul_f32_e32 v5, v32, v2
	v_mul_f32_e32 v2, v33, v2
	v_cvt_pk_bf16_f32 v5, v5, v2
	v_add_u32_e32 v2, 48, v7
	v_xad_u32 v2, v2, v189, v6
	ds_write_b64 v2, v[4:5]
	s_cbranch_vccnz .LBB0_431
	v_lshl_add_u32 v2, v186, 2, s48
	ds_read_b32 v204, v2
	ds_read_b32 v205, v2 offset:256
	ds_read_b32 v206, v2 offset:512
	ds_read_b32 v207, v2 offset:768
	ds_read_b32 v208, v2 offset:1024
	ds_read_b32 v209, v2 offset:1280
	ds_read_b32 v210, v2 offset:1536
	ds_read_b32 v211, v2 offset:1792
	ds_read_b32 v212, v2 offset:2048
	ds_read_b32 v213, v2 offset:2304
	ds_read_b32 v214, v2 offset:2560
	ds_read_b32 v215, v2 offset:2816
	ds_read_b32 v216, v2 offset:3072
	ds_read_b32 v217, v2 offset:3328
	ds_read_b32 v218, v2 offset:3584
	ds_read_b32 v219, v2 offset:3840
	s_add_i32 s10, s58, s22
	s_ashr_i32 s11, s10, 31
	s_lshl_b64 s[10:11], s[10:11], 13
	s_add_u32 s42, s59, s10
	v_lshl_or_b32 v4, v188, 14, v187
	v_and_b32_e32 v5, 1, v186
	s_addc_u32 s43, s60, s11
	v_cmp_eq_u32_e64 s[10:11], 0, v5
	v_ashrrev_i32_e32 v5, 31, v4
	s_waitcnt lgkmcnt(0)
	v_add_f32_e32 v6, v34, v204
	v_lshl_add_u64 v[4:5], v[4:5], 1, s[42:43]
	s_nop 0
	v_mov_b32_dpp v7, v6 quad_perm:[1,0,3,2] row_mask:0xf bank_mask:0xf bound_ctrl:1
	s_and_saveexec_b64 s[42:43], s[10:11]
	s_cbranch_execz .LBB0_398
	v_cvt_pk_bf16_f32 v6, v6, v7
	global_store_dword v[4:5], v6, off
.LBB0_398:
	s_or_b64 exec, exec, s[42:43]
	v_add_f32_e32 v6, v35, v205
	s_nop 1
	v_mov_b32_dpp v7, v6 quad_perm:[1,0,3,2] row_mask:0xf bank_mask:0xf bound_ctrl:1
	s_and_saveexec_b64 s[42:43], s[10:11]
	s_cbranch_execz .LBB0_400
	v_cvt_pk_bf16_f32 v8, v6, v7
	v_add_co_u32_e32 v6, vcc, 0x2000, v4
	s_nop 1
	v_addc_co_u32_e32 v7, vcc, 0, v5, vcc
	global_store_dword v[6:7], v8, off
.LBB0_400:
	s_or_b64 exec, exec, s[42:43]
	v_add_f32_e32 v6, v36, v206
	s_nop 1
	v_mov_b32_dpp v7, v6 quad_perm:[1,0,3,2] row_mask:0xf bank_mask:0xf bound_ctrl:1
	s_and_saveexec_b64 s[42:43], s[10:11]
	s_cbranch_execz .LBB0_402
	v_cvt_pk_bf16_f32 v8, v6, v7
	v_add_co_u32_e32 v6, vcc, 0x4000, v4
	s_nop 1
	v_addc_co_u32_e32 v7, vcc, 0, v5, vcc
	global_store_dword v[6:7], v8, off
.LBB0_402:
	s_or_b64 exec, exec, s[42:43]
	v_add_f32_e32 v6, v37, v207
	s_nop 1
	v_mov_b32_dpp v7, v6 quad_perm:[1,0,3,2] row_mask:0xf bank_mask:0xf bound_ctrl:1
	s_and_saveexec_b64 s[42:43], s[10:11]
	s_cbranch_execz .LBB0_404
	v_cvt_pk_bf16_f32 v8, v6, v7
	v_add_co_u32_e32 v6, vcc, 0x6000, v4
	s_nop 1
	v_addc_co_u32_e32 v7, vcc, 0, v5, vcc
	global_store_dword v[6:7], v8, off
.LBB0_404:
	s_or_b64 exec, exec, s[42:43]
	v_add_f32_e32 v6, v38, v208
	s_nop 1
	v_mov_b32_dpp v7, v6 quad_perm:[1,0,3,2] row_mask:0xf bank_mask:0xf bound_ctrl:1
	s_and_saveexec_b64 s[42:43], s[10:11]
	s_cbranch_execz .LBB0_406
	v_cvt_pk_bf16_f32 v8, v6, v7
	v_add_co_u32_e32 v6, vcc, 0x10000, v4
	s_nop 1
	v_addc_co_u32_e32 v7, vcc, 0, v5, vcc
	global_store_dword v[6:7], v8, off
.LBB0_406:
	s_or_b64 exec, exec, s[42:43]
	v_add_f32_e32 v6, v39, v209
	s_nop 1
	v_mov_b32_dpp v7, v6 quad_perm:[1,0,3,2] row_mask:0xf bank_mask:0xf bound_ctrl:1
	s_and_saveexec_b64 s[42:43], s[10:11]
	s_cbranch_execz .LBB0_408
	v_cvt_pk_bf16_f32 v8, v6, v7
	v_add_co_u32_e32 v6, vcc, 0x12000, v4
	s_nop 1
	v_addc_co_u32_e32 v7, vcc, 0, v5, vcc
	global_store_dword v[6:7], v8, off
.LBB0_408:
	s_or_b64 exec, exec, s[42:43]
	v_add_f32_e32 v6, v40, v210
	s_nop 1
	v_mov_b32_dpp v7, v6 quad_perm:[1,0,3,2] row_mask:0xf bank_mask:0xf bound_ctrl:1
	s_and_saveexec_b64 s[42:43], s[10:11]
	s_cbranch_execz .LBB0_410
	v_cvt_pk_bf16_f32 v8, v6, v7
	v_add_co_u32_e32 v6, vcc, 0x14000, v4
	s_nop 1
	v_addc_co_u32_e32 v7, vcc, 0, v5, vcc
	global_store_dword v[6:7], v8, off
.LBB0_410:
	s_or_b64 exec, exec, s[42:43]
	v_add_f32_e32 v6, v41, v211
	s_nop 1
	v_mov_b32_dpp v7, v6 quad_perm:[1,0,3,2] row_mask:0xf bank_mask:0xf bound_ctrl:1
	s_and_saveexec_b64 s[42:43], s[10:11]
	s_cbranch_execz .LBB0_412
	v_cvt_pk_bf16_f32 v8, v6, v7
	v_add_co_u32_e32 v6, vcc, 0x16000, v4
	s_nop 1
	v_addc_co_u32_e32 v7, vcc, 0, v5, vcc
	global_store_dword v[6:7], v8, off
.LBB0_412:
	s_or_b64 exec, exec, s[42:43]
	v_add_f32_e32 v6, v42, v212
	s_nop 1
	v_mov_b32_dpp v7, v6 quad_perm:[1,0,3,2] row_mask:0xf bank_mask:0xf bound_ctrl:1
	s_and_saveexec_b64 s[42:43], s[10:11]
	s_cbranch_execz .LBB0_414
	v_cvt_pk_bf16_f32 v8, v6, v7
	v_add_co_u32_e32 v6, vcc, 0x20000, v4
	s_nop 1
	v_addc_co_u32_e32 v7, vcc, 0, v5, vcc
	global_store_dword v[6:7], v8, off
.LBB0_414:
	s_or_b64 exec, exec, s[42:43]
	v_add_f32_e32 v6, v43, v213
	s_nop 1
	v_mov_b32_dpp v7, v6 quad_perm:[1,0,3,2] row_mask:0xf bank_mask:0xf bound_ctrl:1
	s_and_saveexec_b64 s[42:43], s[10:11]
	s_cbranch_execz .LBB0_416
	v_cvt_pk_bf16_f32 v8, v6, v7
	v_add_co_u32_e32 v6, vcc, 0x22000, v4
	s_nop 1
	v_addc_co_u32_e32 v7, vcc, 0, v5, vcc
	global_store_dword v[6:7], v8, off
.LBB0_416:
	s_or_b64 exec, exec, s[42:43]
	v_add_f32_e32 v6, v44, v214
	s_nop 1
	v_mov_b32_dpp v7, v6 quad_perm:[1,0,3,2] row_mask:0xf bank_mask:0xf bound_ctrl:1
	s_and_saveexec_b64 s[42:43], s[10:11]
	s_cbranch_execz .LBB0_418
	v_cvt_pk_bf16_f32 v8, v6, v7
	v_add_co_u32_e32 v6, vcc, 0x24000, v4
	s_nop 1
	v_addc_co_u32_e32 v7, vcc, 0, v5, vcc
	global_store_dword v[6:7], v8, off
.LBB0_418:
	s_or_b64 exec, exec, s[42:43]
	v_add_f32_e32 v6, v45, v215
	s_nop 1
	v_mov_b32_dpp v7, v6 quad_perm:[1,0,3,2] row_mask:0xf bank_mask:0xf bound_ctrl:1
	s_and_saveexec_b64 s[42:43], s[10:11]
	s_cbranch_execz .LBB0_420
	v_cvt_pk_bf16_f32 v8, v6, v7
	v_add_co_u32_e32 v6, vcc, 0x26000, v4
	s_nop 1
	v_addc_co_u32_e32 v7, vcc, 0, v5, vcc
	global_store_dword v[6:7], v8, off
.LBB0_420:
	s_or_b64 exec, exec, s[42:43]
	v_add_f32_e32 v6, v46, v216
	s_nop 1
	v_mov_b32_dpp v7, v6 quad_perm:[1,0,3,2] row_mask:0xf bank_mask:0xf bound_ctrl:1
	s_and_saveexec_b64 s[42:43], s[10:11]
	s_cbranch_execz .LBB0_422
	v_cvt_pk_bf16_f32 v8, v6, v7
	v_add_co_u32_e32 v6, vcc, 0x30000, v4
	s_nop 1
	v_addc_co_u32_e32 v7, vcc, 0, v5, vcc
	global_store_dword v[6:7], v8, off
.LBB0_422:
	s_or_b64 exec, exec, s[42:43]
	v_add_f32_e32 v6, v47, v217
	s_nop 1
	v_mov_b32_dpp v7, v6 quad_perm:[1,0,3,2] row_mask:0xf bank_mask:0xf bound_ctrl:1
	s_and_saveexec_b64 s[42:43], s[10:11]
	s_cbranch_execz .LBB0_424
	v_cvt_pk_bf16_f32 v8, v6, v7
	v_add_co_u32_e32 v6, vcc, 0x32000, v4
	s_nop 1
	v_addc_co_u32_e32 v7, vcc, 0, v5, vcc
	global_store_dword v[6:7], v8, off
.LBB0_424:
	s_or_b64 exec, exec, s[42:43]
	v_add_f32_e32 v6, v48, v218
	s_nop 1
	v_mov_b32_dpp v7, v6 quad_perm:[1,0,3,2] row_mask:0xf bank_mask:0xf bound_ctrl:1
	s_and_saveexec_b64 s[42:43], s[10:11]
	s_cbranch_execz .LBB0_426
	v_cvt_pk_bf16_f32 v8, v6, v7
	v_add_co_u32_e32 v6, vcc, 0x34000, v4
	s_nop 1
	v_addc_co_u32_e32 v7, vcc, 0, v5, vcc
	global_store_dword v[6:7], v8, off
.LBB0_426:
	s_or_b64 exec, exec, s[42:43]
	v_add_f32_e32 v2, v49, v219
	s_nop 1
	v_mov_b32_dpp v6, v2 quad_perm:[1,0,3,2] row_mask:0xf bank_mask:0xf bound_ctrl:1
	s_and_saveexec_b64 s[42:43], s[10:11]
	s_cbranch_execz .LBB0_428
	v_add_co_u32_e32 v4, vcc, 0x36000, v4
	v_cvt_pk_bf16_f32 v2, v2, v6
	s_nop 1
	v_addc_co_u32_e32 v5, vcc, 0, v5, vcc
	global_store_dword v[4:5], v2, off

.LBB0_487:
	s_cmp_lt_i32 s72, 6
	s_cselect_b64 s[2:3], -1, 0
	s_and_b64 s[4:5], s[2:3], s[6:7]
	s_andn2_b64 vcc, exec, s[4:5]
	v_lshrrev_b32_e32 v1, 6, v0
	s_cbranch_vccnz .LBB0_656
	s_load_dwordx4 s[8:11], s[0:1], 0xd0
	s_lshl_b32 s2, s76, 3
	v_or_b32_e32 v25, s2, v1
	s_mov_b32 s3, 0xffff
	v_cmp_lt_i32_e32 vcc, s3, v25
	s_and_saveexec_b64 s[6:7], vcc
	s_xor_b64 s[6:7], exec, s[6:7]
	v_lshlrev_b32_e32 v24, 3, v0
	s_or_saveexec_b64 s[6:7], s[6:7]
	s_waitcnt lgkmcnt(0)
	v_mov_b64_e32 v[158:159], s[8:9]
	v_mov_b64_e32 v[4:5], s[10:11]
	s_xor_b64 exec, exec, s[6:7]
	s_cbranch_execz .LBB0_494
	v_mbcnt_lo_u32_b32 v3, -1, 0
	v_mbcnt_hi_u32_b32 v3, -1, v3
	v_and_b32_e32 v4, 64, v3
	v_add_u32_e32 v4, 64, v4
	v_xor_b32_e32 v5, 32, v3
	v_cmp_lt_i32_e32 vcc, v5, v4
	s_load_dwordx2 s[14:15], s[0:1], 0x20
	v_lshlrev_b32_e32 v24, 3, v0
	v_cndmask_b32_e32 v5, v3, v5, vcc
	v_lshlrev_b32_e32 v26, 2, v5
	v_xor_b32_e32 v5, 16, v3
	v_cmp_lt_i32_e32 vcc, v5, v4
	v_bfe_u32 v32, v0, 6, 2
	s_lshl_b32 s3, s80, 3
	v_cndmask_b32_e32 v5, v3, v5, vcc
	v_lshlrev_b32_e32 v27, 2, v5
	v_xor_b32_e32 v5, 8, v3
	v_cmp_lt_i32_e32 vcc, v5, v4
	v_and_b32_e32 v2, 0x1f8, v24
	v_mov_b32_e32 v11, 0
	v_cndmask_b32_e32 v5, v3, v5, vcc
	v_lshlrev_b32_e32 v28, 2, v5
	v_xor_b32_e32 v5, 4, v3
	v_cmp_lt_i32_e32 vcc, v5, v4
	v_lshlrev_b32_e32 v10, 10, v32
	s_add_u32 s12, s10, 0x190000
	v_cndmask_b32_e32 v5, v3, v5, vcc
	v_lshlrev_b32_e32 v29, 2, v5
	v_xor_b32_e32 v5, 2, v3
	v_cmp_lt_i32_e32 vcc, v5, v4
	v_lshl_add_u64 v[6:7], s[8:9], 0, v[10:11]
	v_lshlrev_b32_e32 v10, 1, v2
	v_cndmask_b32_e32 v5, v3, v5, vcc
	v_lshlrev_b32_e32 v30, 2, v5
	v_xor_b32_e32 v5, 1, v3
	v_cmp_lt_i32_e32 vcc, v5, v4
	v_lshlrev_b32_e32 v4, 9, v32
	s_addc_u32 s13, s11, 0
	v_cndmask_b32_e32 v3, v3, v5, vcc
	v_lshlrev_b32_e32 v31, 2, v3
	v_or_b32_e32 v3, v4, v2
	v_lshl_add_u64 v[12:13], v[6:7], 0, v[10:11]
	v_lshlrev_b32_e32 v10, 2, v3
	s_waitcnt lgkmcnt(0)
	v_lshl_add_u64 v[14:15], s[14:15], 0, v[10:11]
	s_add_u32 s14, s10, 0x657d0000
	s_addc_u32 s15, s11, 0
	s_add_u32 s16, s10, 0x65810000
	s_addc_u32 s17, s11, 0
	s_mov_b64 s[18:19], 0
	s_movk_i32 s20, 0x3e00
	s_waitcnt vmcnt(0)
	v_mov_b64_e32 v[16:17], s[10:11]
	v_lshlrev_b32_e32 v18, 1, v4
	v_mov_b32_e32 v19, v11
	v_lshlrev_b32_e32 v20, 1, v2
	v_mov_b32_e32 v21, v11
	s_mov_b32 s21, 0x23512000
	v_mov_b32_e32 v33, 0x358637bd
	s_mov_b32 s22, 0x800000
	s_mov_b32 s23, 0xffff
	s_cmpk_lg_i32 s80, 0x100
	s_cbranch_scc1 .LBB0_492
	v_mov_b32_e32 v111, v11
.Lnorm2:
	v_ashrrev_i32_e32 v22, 2, v25
	v_ashrrev_i32_e32 v23, 12, v25
	v_mad_i64_i32 v[36:37], s[24:25], v22, s20, v[16:17]
	v_and_b32_e32 v10, 0x3ffc, v25
	v_add_u32_e32 v25, s3, v25
	v_and_or_b32 v34, v23, -4, v32
	v_lshl_add_u64 v[36:37], v[36:37], 0, v[18:19]
	v_ashrrev_i32_e32 v23, 31, v22
	v_cmp_lt_i32_e32 vcc, s23, v25
	v_ashrrev_i32_e32 v35, 31, v34
	v_lshlrev_b32_e32 v38, 4, v34
	v_lshl_add_u64 v[40:41], v[36:37], 0, v[20:21]
	v_lshlrev_b64 v[22:23], 13, v[22:23]
	s_or_b64 s[18:19], vcc, s[18:19]
	v_lshlrev_b64 v[44:45], 14, v[34:35]
	v_ashrrev_i32_e32 v39, 31, v38
	v_add_co_u32_e32 v76, vcc, s21, v40
	v_lshl_add_u64 v[42:43], s[16:17], 0, v[10:11]
	v_lshl_add_u64 v[22:23], v[12:13], 0, v[22:23]
	v_or_b32_e32 v46, 1, v38
	v_or_b32_e32 v48, 2, v38
	v_or_b32_e32 v50, 3, v38
	v_or_b32_e32 v52, 4, v38
	v_or_b32_e32 v54, 5, v38
	v_or_b32_e32 v56, 6, v38
	v_or_b32_e32 v58, 7, v38
	v_or_b32_e32 v60, 8, v38
	v_or_b32_e32 v62, 9, v38
	v_or_b32_e32 v64, 10, v38
	v_or_b32_e32 v66, 11, v38
	v_or_b32_e32 v68, 12, v38
	v_or_b32_e32 v70, 13, v38
	v_or_b32_e32 v72, 14, v38
	v_or_b32_e32 v74, 15, v38
	v_addc_co_u32_e32 v77, vcc, 0, v41, vcc
	v_or_b32_e32 v44, v44, v10
	v_lshlrev_b64 v[38:39], 14, v[38:39]
	global_load_dwordx4 v[2:5], v[14:15], off offset:16
	global_load_dwordx4 v[6:9], v[14:15], off
	global_load_dwordx4 v[34:37], v[22:23], off
	v_lshl_add_u64 v[78:79], s[14:15], 0, v[44:45]
	v_lshl_add_u64 v[80:81], v[42:43], 0, v[38:39]
	global_load_dwordx4 v[38:41], v[76:77], off offset:16
	global_load_dword v10, v[78:79], off
	global_load_dword v82, v[80:81], off
	v_ashrrev_i32_e32 v47, 31, v46
	v_ashrrev_i32_e32 v49, 31, v48
	v_ashrrev_i32_e32 v51, 31, v50
	v_ashrrev_i32_e32 v53, 31, v52
	v_ashrrev_i32_e32 v55, 31, v54
	v_ashrrev_i32_e32 v57, 31, v56
	v_ashrrev_i32_e32 v59, 31, v58
	v_ashrrev_i32_e32 v61, 31, v60
	v_ashrrev_i32_e32 v63, 31, v62
	v_ashrrev_i32_e32 v65, 31, v64
	v_ashrrev_i32_e32 v67, 31, v66
	v_ashrrev_i32_e32 v69, 31, v68
	v_ashrrev_i32_e32 v71, 31, v70
	v_ashrrev_i32_e32 v73, 31, v72
	v_ashrrev_i32_e32 v75, 31, v74
	v_lshlrev_b64 v[46:47], 14, v[46:47]
	v_lshlrev_b64 v[48:49], 14, v[48:49]
	v_lshlrev_b64 v[50:51], 14, v[50:51]
	v_lshlrev_b64 v[52:53], 14, v[52:53]
	v_lshlrev_b64 v[54:55], 14, v[54:55]
	v_lshlrev_b64 v[56:57], 14, v[56:57]
	v_lshlrev_b64 v[58:59], 14, v[58:59]
	v_lshlrev_b64 v[60:61], 14, v[60:61]
	v_lshlrev_b64 v[62:63], 14, v[62:63]
	v_lshlrev_b64 v[64:65], 14, v[64:65]
	v_lshlrev_b64 v[66:67], 14, v[66:67]
	v_lshlrev_b64 v[68:69], 14, v[68:69]
	v_lshlrev_b64 v[70:71], 14, v[70:71]
	v_lshlrev_b64 v[72:73], 14, v[72:73]
	v_lshlrev_b64 v[74:75], 14, v[74:75]
	v_lshl_add_u64 v[44:45], s[12:13], 0, v[44:45]
	v_lshl_add_u64 v[46:47], v[42:43], 0, v[46:47]
	v_lshl_add_u64 v[48:49], v[42:43], 0, v[48:49]
	v_lshl_add_u64 v[50:51], v[42:43], 0, v[50:51]
	v_lshl_add_u64 v[52:53], v[42:43], 0, v[52:53]
	v_lshl_add_u64 v[54:55], v[42:43], 0, v[54:55]
	v_lshl_add_u64 v[56:57], v[42:43], 0, v[56:57]
	v_lshl_add_u64 v[58:59], v[42:43], 0, v[58:59]
	v_lshl_add_u64 v[60:61], v[42:43], 0, v[60:61]
	v_lshl_add_u64 v[62:63], v[42:43], 0, v[62:63]
	v_lshl_add_u64 v[64:65], v[42:43], 0, v[64:65]
	v_lshl_add_u64 v[66:67], v[42:43], 0, v[66:67]
	v_lshl_add_u64 v[68:69], v[42:43], 0, v[68:69]
	v_lshl_add_u64 v[70:71], v[42:43], 0, v[70:71]
	v_lshl_add_u64 v[72:73], v[42:43], 0, v[72:73]
	v_lshl_add_u64 v[42:43], v[42:43], 0, v[74:75]
	global_load_dword v74, v[46:47], off
	global_load_dword v75, v[44:45], off
	global_load_dword v76, v[48:49], off
	global_load_dword v77, v[50:51], off
	global_load_dword v78, v[52:53], off
	global_load_dword v79, v[54:55], off
	global_load_dword v80, v[56:57], off
	global_load_dword v81, v[58:59], off
	global_load_dword v83, v[60:61], off
	global_load_dword v84, v[62:63], off
	global_load_dword v85, v[64:65], off
	global_load_dword v86, v[66:67], off
	global_load_dword v87, v[68:69], off
	global_load_dword v88, v[70:71], off
	global_load_dword v89, v[72:73], off
	global_load_dword v44, v[42:43], off
	v_ashrrev_i32_e32 v122, 2, v25
	v_ashrrev_i32_e32 v123, 12, v25
	v_mad_i64_i32 v[136:137], s[24:25], v122, s20, v[16:17]
	v_and_b32_e32 v110, 0x3ffc, v25
	v_add_u32_e32 v25, s3, v25
	v_and_or_b32 v134, v123, -4, v32
	v_lshl_add_u64 v[136:137], v[136:137], 0, v[18:19]
	v_ashrrev_i32_e32 v123, 31, v122
	v_cmp_lt_i32_e32 vcc, s23, v25
	v_ashrrev_i32_e32 v135, 31, v134
	v_lshlrev_b32_e32 v138, 4, v134
	v_lshl_add_u64 v[140:141], v[136:137], 0, v[20:21]
	v_lshlrev_b64 v[122:123], 13, v[122:123]
	s_or_b64 s[18:19], vcc, s[18:19]
	v_lshlrev_b64 v[144:145], 14, v[134:135]
	v_ashrrev_i32_e32 v139, 31, v138
	v_add_co_u32_e32 v176, vcc, s21, v140
	v_lshl_add_u64 v[142:143], s[16:17], 0, v[110:111]
	v_lshl_add_u64 v[122:123], v[12:13], 0, v[122:123]
	v_or_b32_e32 v146, 1, v138
	v_or_b32_e32 v148, 2, v138
	v_or_b32_e32 v150, 3, v138
	v_or_b32_e32 v152, 4, v138
	v_or_b32_e32 v154, 5, v138
	v_or_b32_e32 v156, 6, v138
	v_or_b32_e32 v158, 7, v138
	v_or_b32_e32 v160, 8, v138
	v_or_b32_e32 v162, 9, v138
	v_or_b32_e32 v164, 10, v138
	v_or_b32_e32 v166, 11, v138
	v_or_b32_e32 v168, 12, v138
	v_or_b32_e32 v170, 13, v138
	v_or_b32_e32 v172, 14, v138
	v_or_b32_e32 v174, 15, v138
	v_addc_co_u32_e32 v177, vcc, 0, v141, vcc
	v_or_b32_e32 v144, v144, v110
	v_lshlrev_b64 v[138:139], 14, v[138:139]
	global_load_dwordx4 v[102:105], v[14:15], off offset:16
	global_load_dwordx4 v[106:109], v[14:15], off
	global_load_dwordx4 v[134:137], v[122:123], off
	v_lshl_add_u64 v[178:179], s[14:15], 0, v[144:145]
	v_lshl_add_u64 v[180:181], v[142:143], 0, v[138:139]
	global_load_dwordx4 v[138:141], v[176:177], off offset:16
	global_load_dword v110, v[178:179], off
	global_load_dword v182, v[180:181], off
	v_ashrrev_i32_e32 v147, 31, v146
	v_ashrrev_i32_e32 v149, 31, v148
	v_ashrrev_i32_e32 v151, 31, v150
	v_ashrrev_i32_e32 v153, 31, v152
	v_ashrrev_i32_e32 v155, 31, v154
	v_ashrrev_i32_e32 v157, 31, v156
	v_ashrrev_i32_e32 v159, 31, v158
	v_ashrrev_i32_e32 v161, 31, v160
	v_ashrrev_i32_e32 v163, 31, v162
	v_ashrrev_i32_e32 v165, 31, v164
	v_ashrrev_i32_e32 v167, 31, v166
	v_ashrrev_i32_e32 v169, 31, v168
	v_ashrrev_i32_e32 v171, 31, v170
	v_ashrrev_i32_e32 v173, 31, v172
	v_ashrrev_i32_e32 v175, 31, v174
	v_lshlrev_b64 v[146:147], 14, v[146:147]
	v_lshlrev_b64 v[148:149], 14, v[148:149]
	v_lshlrev_b64 v[150:151], 14, v[150:151]
	v_lshlrev_b64 v[152:153], 14, v[152:153]
	v_lshlrev_b64 v[154:155], 14, v[154:155]
	v_lshlrev_b64 v[156:157], 14, v[156:157]
	v_lshlrev_b64 v[158:159], 14, v[158:159]
	v_lshlrev_b64 v[160:161], 14, v[160:161]
	v_lshlrev_b64 v[162:163], 14, v[162:163]
	v_lshlrev_b64 v[164:165], 14, v[164:165]
	v_lshlrev_b64 v[166:167], 14, v[166:167]
	v_lshlrev_b64 v[168:169], 14, v[168:169]
	v_lshlrev_b64 v[170:171], 14, v[170:171]
	v_lshlrev_b64 v[172:173], 14, v[172:173]
	v_lshlrev_b64 v[174:175], 14, v[174:175]
	v_lshl_add_u64 v[144:145], s[12:13], 0, v[144:145]
	v_lshl_add_u64 v[146:147], v[142:143], 0, v[146:147]
	v_lshl_add_u64 v[148:149], v[142:143], 0, v[148:149]
	v_lshl_add_u64 v[150:151], v[142:143], 0, v[150:151]
	v_lshl_add_u64 v[152:153], v[142:143], 0, v[152:153]
	v_lshl_add_u64 v[154:155], v[142:143], 0, v[154:155]
	v_lshl_add_u64 v[156:157], v[142:143], 0, v[156:157]
	v_lshl_add_u64 v[158:159], v[142:143], 0, v[158:159]
	v_lshl_add_u64 v[160:161], v[142:143], 0, v[160:161]
	v_lshl_add_u64 v[162:163], v[142:143], 0, v[162:163]
	v_lshl_add_u64 v[164:165], v[142:143], 0, v[164:165]
	v_lshl_add_u64 v[166:167], v[142:143], 0, v[166:167]
	v_lshl_add_u64 v[168:169], v[142:143], 0, v[168:169]
	v_lshl_add_u64 v[170:171], v[142:143], 0, v[170:171]
	v_lshl_add_u64 v[172:173], v[142:143], 0, v[172:173]
	v_lshl_add_u64 v[142:143], v[142:143], 0, v[174:175]
	global_load_dword v174, v[146:147], off
	global_load_dword v175, v[144:145], off
	global_load_dword v176, v[148:149], off
	global_load_dword v177, v[150:151], off
	global_load_dword v178, v[152:153], off
	global_load_dword v179, v[154:155], off
	global_load_dword v180, v[156:157], off
	global_load_dword v181, v[158:159], off
	global_load_dword v183, v[160:161], off
	global_load_dword v184, v[162:163], off
	global_load_dword v185, v[164:165], off
	global_load_dword v186, v[166:167], off
	global_load_dword v187, v[168:169], off
	global_load_dword v188, v[170:171], off
	global_load_dword v189, v[172:173], off
	global_load_dword v144, v[142:143], off
	s_waitcnt vmcnt(41)
	v_lshlrev_b32_e32 v45, 16, v34
	v_and_b32_e32 v46, 0xffff0000, v34
	v_lshlrev_b32_e32 v47, 16, v35
	s_waitcnt vmcnt(38)
	v_add_f32_e32 v10, v10, v82
	v_and_b32_e32 v48, 0xffff0000, v35
	v_and_b32_e32 v35, 0xffff0000, v36
	v_lshlrev_b32_e32 v34, 16, v36
	v_lshlrev_b32_e32 v36, 16, v38
	v_and_b32_e32 v43, 0xffff0000, v37
	v_lshlrev_b32_e32 v42, 16, v37
	v_and_b32_e32 v37, 0xffff0000, v38
	v_lshlrev_b32_e32 v38, 16, v39
	v_mul_f32_e32 v36, 0xbfb8aa3b, v36
	v_mul_f32_e32 v38, 0xbfb8aa3b, v38
	v_exp_f32_e32 v36, v36
	v_exp_f32_e32 v38, v38
	v_and_b32_e32 v39, 0xffff0000, v39
	v_mul_f32_e32 v39, 0xbfb8aa3b, v39
	v_add_f32_e32 v36, 1.0, v36
	v_mul_f32_e32 v37, 0xbfb8aa3b, v37
	s_waitcnt vmcnt(37)
	v_add_f32_e32 v10, v10, v74
	s_waitcnt vmcnt(36)
	v_max_f32_e32 v51, v75, v75
	s_waitcnt vmcnt(35)
	v_add_f32_e32 v10, v10, v76
	s_waitcnt vmcnt(34)
	v_add_f32_e32 v10, v10, v77
	s_waitcnt vmcnt(33)
	v_add_f32_e32 v10, v10, v78
	s_waitcnt vmcnt(32)
	v_add_f32_e32 v10, v10, v79
	s_waitcnt vmcnt(31)
	v_add_f32_e32 v10, v10, v80
	s_waitcnt vmcnt(30)
	v_add_f32_e32 v10, v10, v81
	s_waitcnt vmcnt(29)
	v_add_f32_e32 v10, v10, v83
	s_waitcnt vmcnt(28)
	v_add_f32_e32 v10, v10, v84
	s_waitcnt vmcnt(27)
	v_add_f32_e32 v10, v10, v85
	s_waitcnt vmcnt(26)
	v_add_f32_e32 v10, v10, v86
	s_waitcnt vmcnt(25)
	v_add_f32_e32 v10, v10, v87
	s_waitcnt vmcnt(24)
	v_add_f32_e32 v10, v10, v88
	s_waitcnt vmcnt(23)
	v_add_f32_e32 v10, v10, v89
	v_exp_f32_e32 v39, v39
	v_add_f32_e32 v38, 1.0, v38
	v_rcp_f32_e32 v52, v36
	v_lshlrev_b32_e32 v49, 16, v40
	v_and_b32_e32 v40, 0xffff0000, v40
	v_exp_f32_e32 v37, v37
	v_rcp_f32_e32 v54, v38
	v_mul_f32_e32 v40, 0xbfb8aa3b, v40
	v_exp_f32_e32 v40, v40
	v_add_f32_e32 v39, 1.0, v39
	v_add_f32_e32 v37, 1.0, v37
	v_rcp_f32_e32 v55, v39
	v_rcp_f32_e32 v53, v37
	v_add_f32_e32 v40, 1.0, v40
	v_rcp_f32_e32 v56, v40
	s_waitcnt vmcnt(22)
	v_add_f32_e32 v10, v10, v44
	v_max_f32_e64 v10, |v10|, v51
	v_div_scale_f32 v36, s[24:25], v10, v10, 1.0
	v_rcp_f32_e32 v38, v36
	v_div_scale_f32 v37, vcc, 1.0, v10, 1.0
	v_lshlrev_b32_e32 v50, 16, v41
	v_fma_f32 v39, -v36, v38, 1.0
	v_fmac_f32_e32 v38, v39, v38
	v_mul_f32_e32 v39, v37, v38
	v_fma_f32 v40, -v36, v39, v37
	v_fmac_f32_e32 v39, v40, v38
	v_fma_f32 v36, -v36, v39, v37
	v_div_fmas_f32 v36, v36, v38, v39
	v_and_b32_e32 v41, 0xffff0000, v41
	v_div_fixup_f32 v10, v36, v10, 1.0
	v_mul_f32_e32 v41, 0xbfb8aa3b, v41
	v_mul_f32_e32 v44, v10, v45
	v_mul_f32_e32 v45, v10, v46
	v_exp_f32_e32 v41, v41
	v_mul_f32_e32 v46, v10, v47
	v_mul_f32_e32 v47, v10, v48
	v_pk_mul_f32 v[34:35], v[10:11], v[34:35] op_sel_hi:[0,1]
	v_pk_mul_f32 v[36:37], v[10:11], v[42:43] op_sel_hi:[0,1]
	v_mul_f32_e32 v10, v45, v45
	v_fmac_f32_e32 v10, v44, v44
	v_fmac_f32_e32 v10, v46, v46
	v_pk_mul_f32 v[38:39], v[34:35], v[34:35]
	v_fmac_f32_e32 v10, v47, v47
	v_add_f32_e32 v41, 1.0, v41
	v_add_f32_e32 v10, v38, v10
	v_rcp_f32_e32 v57, v41
	v_pk_mul_f32 v[40:41], v[36:37], v[36:37]
	v_add_f32_e32 v10, v39, v10
	v_add_f32_e32 v10, v40, v10
	v_add_f32_e32 v10, v41, v10
	ds_bpermute_b32 v38, v26, v10
	v_mul_f32_e32 v49, 0xbfb8aa3b, v49
	v_mul_f32_e32 v50, 0xbfb8aa3b, v50
	v_exp_f32_e32 v49, v49
	v_exp_f32_e32 v50, v50
	s_waitcnt lgkmcnt(0)
	v_add_f32_e32 v10, v10, v38
	ds_bpermute_b32 v38, v27, v10
	v_add_f32_e32 v49, 1.0, v49
	v_add_f32_e32 v50, 1.0, v50
	v_rcp_f32_e32 v49, v49
	v_rcp_f32_e32 v50, v50
	s_waitcnt lgkmcnt(0)
	v_add_f32_e32 v10, v10, v38
	ds_bpermute_b32 v38, v28, v10
	s_waitcnt lgkmcnt(0)
	v_add_f32_e32 v10, v10, v38
	ds_bpermute_b32 v38, v29, v10
	s_waitcnt lgkmcnt(0)
	v_add_f32_e32 v10, v10, v38
	ds_bpermute_b32 v38, v30, v10
	s_waitcnt lgkmcnt(0)
	v_add_f32_e32 v10, v10, v38
	ds_bpermute_b32 v38, v31, v10
	s_waitcnt lgkmcnt(0)
	v_add_f32_e32 v10, v10, v38
	v_fmamk_f32 v10, v10, 0x3b000000, v33
	v_mul_f32_e32 v38, 0x4b800000, v10
	v_cmp_gt_f32_e32 vcc, s22, v10
	s_nop 1
	v_cndmask_b32_e32 v10, v10, v38, vcc
	v_rsq_f32_e32 v10, v10
	s_nop 0
	v_mul_f32_e32 v38, 0x45800000, v10
	v_cndmask_b32_e32 v10, v10, v38, vcc
	v_mul_f32_e32 v38, v44, v10
	v_mul_f32_e32 v39, v45, v10
	v_mul_f32_e32 v40, v46, v10
	v_mul_f32_e32 v41, v47, v10
	v_mul_f32_e32 v34, v34, v10
	v_mul_f32_e32 v35, v35, v10
	v_mul_f32_e32 v36, v36, v10
	v_mul_f32_e32 v10, v37, v10
	v_mul_f32_e32 v5, v5, v10
	v_mul_f32_e32 v6, v6, v38
	v_mul_f32_e32 v7, v7, v39
	v_mul_f32_e32 v8, v8, v40
	v_mul_f32_e32 v9, v9, v41
	v_mul_f32_e32 v2, v2, v34
	v_mul_f32_e32 v3, v3, v35
	v_mul_f32_e32 v4, v4, v36
	v_mul_f32_e32 v5, v57, v5
	v_mul_f32_e32 v6, v52, v6
	v_mul_f32_e32 v7, v53, v7
	v_mul_f32_e32 v8, v54, v8
	v_mul_f32_e32 v9, v55, v9
	v_mul_f32_e32 v10, v49, v2
	v_mul_f32_e32 v34, v56, v3
	v_mul_f32_e32 v35, v50, v4
	v_cvt_pk_bf16_f32 v2, v6, v7
	v_cvt_pk_bf16_f32 v3, v8, v9
	v_cvt_pk_bf16_f32 v4, v10, v34
	v_cvt_pk_bf16_f32 v5, v35, v5
	global_store_dwordx4 v[22:23], v[2:5], off
	s_waitcnt vmcnt(20)
	v_lshlrev_b32_e32 v145, 16, v134
	v_and_b32_e32 v146, 0xffff0000, v134
	v_lshlrev_b32_e32 v147, 16, v135
	s_waitcnt vmcnt(17)
	v_add_f32_e32 v110, v110, v182
	v_and_b32_e32 v148, 0xffff0000, v135
	v_and_b32_e32 v135, 0xffff0000, v136
	v_lshlrev_b32_e32 v134, 16, v136
	v_lshlrev_b32_e32 v136, 16, v138
	v_and_b32_e32 v143, 0xffff0000, v137
	v_lshlrev_b32_e32 v142, 16, v137
	v_and_b32_e32 v137, 0xffff0000, v138
	v_lshlrev_b32_e32 v138, 16, v139
	v_mul_f32_e32 v136, 0xbfb8aa3b, v136
	v_mul_f32_e32 v138, 0xbfb8aa3b, v138
	v_exp_f32_e32 v136, v136
	v_exp_f32_e32 v138, v138
	v_and_b32_e32 v139, 0xffff0000, v139
	v_mul_f32_e32 v139, 0xbfb8aa3b, v139
	v_add_f32_e32 v136, 1.0, v136
	v_mul_f32_e32 v137, 0xbfb8aa3b, v137
	s_waitcnt vmcnt(16)
	v_add_f32_e32 v110, v110, v174
	s_waitcnt vmcnt(15)
	v_max_f32_e32 v151, v175, v175
	s_waitcnt vmcnt(14)
	v_add_f32_e32 v110, v110, v176
	s_waitcnt vmcnt(13)
	v_add_f32_e32 v110, v110, v177
	s_waitcnt vmcnt(12)
	v_add_f32_e32 v110, v110, v178
	s_waitcnt vmcnt(11)
	v_add_f32_e32 v110, v110, v179
	s_waitcnt vmcnt(10)
	v_add_f32_e32 v110, v110, v180
	s_waitcnt vmcnt(9)
	v_add_f32_e32 v110, v110, v181
	s_waitcnt vmcnt(8)
	v_add_f32_e32 v110, v110, v183
	s_waitcnt vmcnt(7)
	v_add_f32_e32 v110, v110, v184
	s_waitcnt vmcnt(6)
	v_add_f32_e32 v110, v110, v185
	s_waitcnt vmcnt(5)
	v_add_f32_e32 v110, v110, v186
	s_waitcnt vmcnt(4)
	v_add_f32_e32 v110, v110, v187
	s_waitcnt vmcnt(3)
	v_add_f32_e32 v110, v110, v188
	s_waitcnt vmcnt(2)
	v_add_f32_e32 v110, v110, v189
	v_exp_f32_e32 v139, v139
	v_add_f32_e32 v138, 1.0, v138
	v_rcp_f32_e32 v152, v136
	v_lshlrev_b32_e32 v149, 16, v140
	v_and_b32_e32 v140, 0xffff0000, v140
	v_exp_f32_e32 v137, v137
	v_rcp_f32_e32 v154, v138
	v_mul_f32_e32 v140, 0xbfb8aa3b, v140
	v_exp_f32_e32 v140, v140
	v_add_f32_e32 v139, 1.0, v139
	v_add_f32_e32 v137, 1.0, v137
	v_rcp_f32_e32 v155, v139
	v_rcp_f32_e32 v153, v137
	v_add_f32_e32 v140, 1.0, v140
	v_rcp_f32_e32 v156, v140
	s_waitcnt vmcnt(1)
	v_add_f32_e32 v110, v110, v144
	v_max_f32_e64 v110, |v110|, v151
	v_div_scale_f32 v136, s[24:25], v110, v110, 1.0
	v_rcp_f32_e32 v138, v136
	v_div_scale_f32 v137, vcc, 1.0, v110, 1.0
	v_lshlrev_b32_e32 v150, 16, v141
	v_fma_f32 v139, -v136, v138, 1.0
	v_fmac_f32_e32 v138, v139, v138
	v_mul_f32_e32 v139, v137, v138
	v_fma_f32 v140, -v136, v139, v137
	v_fmac_f32_e32 v139, v140, v138
	v_fma_f32 v136, -v136, v139, v137
	v_div_fmas_f32 v136, v136, v138, v139
	v_and_b32_e32 v141, 0xffff0000, v141
	v_div_fixup_f32 v110, v136, v110, 1.0
	v_mul_f32_e32 v141, 0xbfb8aa3b, v141
	v_mul_f32_e32 v144, v110, v145
	v_mul_f32_e32 v145, v110, v146
	v_exp_f32_e32 v141, v141
	v_mul_f32_e32 v146, v110, v147
	v_mul_f32_e32 v147, v110, v148
	v_pk_mul_f32 v[134:135], v[110:111], v[134:135] op_sel_hi:[0,1]
	v_pk_mul_f32 v[136:137], v[110:111], v[142:143] op_sel_hi:[0,1]
	v_mul_f32_e32 v110, v145, v145
	v_fmac_f32_e32 v110, v144, v144
	v_fmac_f32_e32 v110, v146, v146
	v_pk_mul_f32 v[138:139], v[134:135], v[134:135]
	v_fmac_f32_e32 v110, v147, v147
	v_add_f32_e32 v141, 1.0, v141
	v_add_f32_e32 v110, v138, v110
	v_rcp_f32_e32 v157, v141
	v_pk_mul_f32 v[140:141], v[136:137], v[136:137]
	v_add_f32_e32 v110, v139, v110
	v_add_f32_e32 v110, v140, v110
	v_add_f32_e32 v110, v141, v110
	ds_bpermute_b32 v138, v26, v110
	v_mul_f32_e32 v149, 0xbfb8aa3b, v149
	v_mul_f32_e32 v150, 0xbfb8aa3b, v150
	v_exp_f32_e32 v149, v149
	v_exp_f32_e32 v150, v150
	s_waitcnt lgkmcnt(0)
	v_add_f32_e32 v110, v110, v138
	ds_bpermute_b32 v138, v27, v110
	v_add_f32_e32 v149, 1.0, v149
	v_add_f32_e32 v150, 1.0, v150
	v_rcp_f32_e32 v149, v149
	v_rcp_f32_e32 v150, v150
	s_waitcnt lgkmcnt(0)
	v_add_f32_e32 v110, v110, v138
	ds_bpermute_b32 v138, v28, v110
	s_waitcnt lgkmcnt(0)
	v_add_f32_e32 v110, v110, v138
	ds_bpermute_b32 v138, v29, v110
	s_waitcnt lgkmcnt(0)
	v_add_f32_e32 v110, v110, v138
	ds_bpermute_b32 v138, v30, v110
	s_waitcnt lgkmcnt(0)
	v_add_f32_e32 v110, v110, v138
	ds_bpermute_b32 v138, v31, v110
	s_waitcnt lgkmcnt(0)
	v_add_f32_e32 v110, v110, v138
	v_fmamk_f32 v110, v110, 0x3b000000, v33
	v_mul_f32_e32 v138, 0x4b800000, v110
	v_cmp_gt_f32_e32 vcc, s22, v110
	s_nop 1
	v_cndmask_b32_e32 v110, v110, v138, vcc
	v_rsq_f32_e32 v110, v110
	s_nop 0
	v_mul_f32_e32 v138, 0x45800000, v110
	v_cndmask_b32_e32 v110, v110, v138, vcc
	v_mul_f32_e32 v138, v144, v110
	v_mul_f32_e32 v139, v145, v110
	v_mul_f32_e32 v140, v146, v110
	v_mul_f32_e32 v141, v147, v110
	v_mul_f32_e32 v134, v134, v110
	v_mul_f32_e32 v135, v135, v110
	v_mul_f32_e32 v136, v136, v110
	v_mul_f32_e32 v110, v137, v110
	v_mul_f32_e32 v105, v105, v110
	v_mul_f32_e32 v106, v106, v138
	v_mul_f32_e32 v107, v107, v139
	v_mul_f32_e32 v108, v108, v140
	v_mul_f32_e32 v109, v109, v141
	v_mul_f32_e32 v102, v102, v134
	v_mul_f32_e32 v103, v103, v135
	v_mul_f32_e32 v104, v104, v136
	v_mul_f32_e32 v105, v157, v105
	v_mul_f32_e32 v106, v152, v106
	v_mul_f32_e32 v107, v153, v107
	v_mul_f32_e32 v108, v154, v108
	v_mul_f32_e32 v109, v155, v109
	v_mul_f32_e32 v110, v149, v102
	v_mul_f32_e32 v134, v156, v103
	v_mul_f32_e32 v135, v150, v104
	v_cvt_pk_bf16_f32 v102, v106, v107
	v_cvt_pk_bf16_f32 v103, v108, v109
	v_cvt_pk_bf16_f32 v104, v110, v134
	v_cvt_pk_bf16_f32 v105, v135, v105
	global_store_dwordx4 v[122:123], v[102:105], off
	s_andn2_b64 exec, exec, s[18:19]
	s_cbranch_execnz .Lnorm2
	s_branch .Lnorm_done

.Lnorm_done:
	s_or_b64 exec, exec, s[18:19]
	v_mov_b64_e32 v[158:159], s[8:9]
	v_mov_b64_e32 v[4:5], s[10:11]
